# v33: v32 + phase-19 final combine: slot-map/affinity words loaded one iteration ahead as in phase 10
# baseline (speedup 1.0000x reference)
.LBB0_2005:
	s_ashr_i32 s3, s2, 31
	s_lshl_b64 s[0:1], s[2:3], 6
	v_lshl_add_u64 v[18:19], v[52:53], 0, s[0:1]
	s_lshl_b64 s[0:1], s[2:3], 11
	v_lshl_add_u64 v[58:59], v[56:57], 0, s[0:1]
	v_lshl_add_u64 v[16:17], s[2:3], 2, v[50:51]
	v_add_co_u32_e32 v60, vcc, 0x1000, v58
	s_cmp_eq_u32 s8, 0
	s_cbranch_scc1 .Lcp_first19
	v_mov_b32_e32 v89, v122
	v_mov_b32_e32 v90, v123
	s_branch .Lcp_go19
.Lcp_first19:
	global_load_dword v89, v[16:17], off
	global_load_dword v90, v[18:19], off
	s_waitcnt vmcnt(0)
.Lcp_go19:
	global_load_dword v122, v[16:17], off offset:16
	global_load_dword v123, v[18:19], off offset:256
	global_load_dwordx4 v[44:47], v[58:59], off
	global_load_dwordx4 v[40:43], v[58:59], off offset:1024
	global_load_dwordx4 v[36:39], v[58:59], off offset:2048
	v_addc_co_u32_e32 v61, vcc, 0, v59, vcc
	global_load_dwordx4 v[32:35], v[58:59], off offset:3072
	global_load_dwordx4 v[28:31], v[60:61], off
	global_load_dwordx4 v[24:27], v[60:61], off offset:1024
	global_load_dwordx4 v[20:23], v[60:61], off offset:2048
	global_load_dwordx4 v[16:19], v[60:61], off offset:3072
	v_cmp_lt_i32_e64 s[0:1], -1, v89
	s_and_b32 s11, s0, 0xffff
	s_cmp_eq_u32 s11, 0
	s_cbranch_scc1 .LBB0_2010
	v_mov_b32_e32 v64, 0
	v_mov_b32_e32 v65, v64
	v_mov_b32_e32 v58, v64
	v_mov_b32_e32 v59, v64
	v_mov_b32_e32 v60, v64
	v_mov_b32_e32 v61, v64
	v_mov_b32_e32 v62, v64
	v_mov_b32_e32 v63, v64
	v_mov_b32_e32 v68, v64
	v_mov_b32_e32 v69, v64
	v_mov_b32_e32 v66, v64
	v_mov_b32_e32 v67, v64
	v_mov_b32_e32 v72, v64
	v_mov_b32_e32 v73, v64
	v_mov_b32_e32 v70, v64
	v_mov_b32_e32 v71, v64
	s_branch .LBB0_2008

.LBB0_2010:
	s_waitcnt vmcnt(0)
	v_mov_b32_e32 v71, 0
	v_mov_b32_e32 v70, v71
	v_mov_b32_e32 v73, v71
	v_mov_b32_e32 v72, v71
	v_mov_b32_e32 v67, v71
	v_mov_b32_e32 v66, v71
	v_mov_b32_e32 v69, v71
	v_mov_b32_e32 v68, v71
	v_mov_b32_e32 v63, v71
	v_mov_b32_e32 v62, v71
	v_mov_b32_e32 v61, v71
	v_mov_b32_e32 v60, v71
	v_mov_b32_e32 v59, v71
	v_mov_b32_e32 v58, v71
	v_mov_b32_e32 v65, v71
	v_mov_b32_e32 v64, v71
